# combo12 + all sample scans on GEMM-less workgroups + counted waits in the scan loops + attention load hoists (k_norm, K/V rotate, gate, q)
# speedup vs baseline: 1.0167x; 1.0052x over previous
; #define SC_BAR() do { asm volatile("s_waitcnt lgkmcnt(0)" ::: "memory"); __builtin_amdgcn_s_barrier(); asm volatile("" ::: "memory"); } while (0)
; template <bool PROMPT>
; __device__ __forceinline__ void scan_block(const Params& p, LAS unsigned char* lds, int chs0, int nsteps, const float* s0, float* sfin, int rowbase, int ntok, int h, int half) {
;     ...
;         if constexpr (PROMPT) {
;             SC_LOAD(A, chs0 + 1); SC_LOAD(Bq, chs0 + 2);
;             for (int n = 0; n < nsteps; n += 2) {
;                 SC_STORE(A, 1);  { const int c = (n + 3 < nsteps) ? n + 3 : nsteps - 1; SC_LOAD(A, chs0 + c); }  SC_BAR();
;                 SC_STORE(Bq, 0); { const int c = (n + 4 < nsteps) ? n + 4 : nsteps - 1; SC_LOAD(Bq, chs0 + c); } SC_BAR();
;             }
.LBB0_599:
	s_add_i32 s9, s9, 2
	s_min_u32 s6, s9, 28
	s_min_u32 s10, s9, 27
	s_add_i32 s14, s17, s6
	s_mov_b32 s11, s7
	s_add_i32 s18, s8, s10
	s_lshl_b32 s10, s14, 14
	s_waitcnt vmcnt(14)
	ds_write_b128 v120, v[8:11] offset:62464
	ds_write_b128 v122, v[12:15]
	ds_write_b128 v123, v[44:47]
	ds_write_b128 v124, v[72:75] offset:62464
	ds_write_b128 v122, v[84:87] offset:4352
	ds_write_b128 v123, v[92:95] offset:4608
	ds_write_b128 v125, v[76:79] offset:62464
	ds_write_b128 v122, v[80:83] offset:8704
	ds_write_b128 v123, v[88:91] offset:9216
	ds_write_b128 v126, v[96:99] offset:62464
	ds_write_b128 v122, v[100:103] offset:13056
	ds_write_b128 v123, v[104:107] offset:13824
	ds_write_b128 v127, v[64:67]
	ds_write_b128 v127, v[108:111] offset:4608
	v_lshl_add_u64 v[64:65], v[112:113], 0, s[10:11]
	v_add_co_u32_e32 v88, vcc, s5, v64
	v_lshl_add_u64 v[66:67], v[114:115], 0, s[10:11]
	s_nop 0
	v_addc_co_u32_e32 v89, vcc, 0, v65, vcc
	v_add_co_u32_e32 v90, vcc, s5, v66
	v_lshl_add_u64 v[72:73], v[116:117], 0, s[10:11]
	s_nop 0
	v_addc_co_u32_e32 v91, vcc, 0, v67, vcc
	v_add_co_u32_e32 v96, vcc, s5, v72
	s_lshl_b32 s6, s14, 13
	s_nop 0
	v_addc_co_u32_e32 v97, vcc, 0, v73, vcc
	v_add_co_u32_e32 v98, vcc, s16, v64
	v_lshl_add_u64 v[74:75], v[118:119], 0, s[6:7]
	s_nop 0
	v_addc_co_u32_e32 v99, vcc, 0, v65, vcc
	v_add_co_u32_e32 v100, vcc, s16, v66
	s_mov_b32 s15, s7
	s_nop 0
	v_addc_co_u32_e32 v101, vcc, 0, v67, vcc
	v_add_co_u32_e32 v104, vcc, s16, v72
	s_lshl_b32 s14, s18, 14
	s_nop 0
	v_addc_co_u32_e32 v105, vcc, 0, v73, vcc
	v_add_co_u32_e32 v108, vcc, s1, v74
	v_lshl_add_u64 v[128:129], v[112:113], 0, s[14:15]
	s_nop 0
	v_addc_co_u32_e32 v109, vcc, 0, v75, vcc
	v_add_co_u32_e32 v134, vcc, s5, v128
	v_lshl_add_u64 v[130:131], v[114:115], 0, s[14:15]
	s_nop 0
	v_addc_co_u32_e32 v135, vcc, 0, v129, vcc
	global_load_dwordx4 v[8:11], v[64:65], off
	global_load_dwordx4 v[12:15], v[66:67], off
	global_load_dwordx4 v[44:47], v[72:73], off
	v_lshl_add_u64 v[132:133], v[116:117], 0, s[14:15]
	global_load_dwordx4 v[64:67], v[74:75], off
	s_nop 0
	global_load_dwordx4 v[72:75], v[88:89], off offset:-4096
	global_load_dwordx4 v[76:79], v[88:89], off
	global_load_dwordx4 v[84:87], v[90:91], off offset:-4096
	global_load_dwordx4 v[80:83], v[90:91], off
	global_load_dwordx4 v[92:95], v[96:97], off offset:-4096
	s_nop 0
	global_load_dwordx4 v[88:91], v[96:97], off
	s_nop 0
	global_load_dwordx4 v[96:99], v[98:99], off
	s_nop 0
	global_load_dwordx4 v[100:103], v[100:101], off
	s_nop 0
	global_load_dwordx4 v[104:107], v[104:105], off
	s_nop 0
	global_load_dwordx4 v[108:111], v[108:109], off
	s_waitcnt lgkmcnt(0)
	s_barrier
	s_waitcnt vmcnt(14)
	ds_write_b128 v120, v[0:3]
	ds_write_b128 v120, v[4:7] offset:17408
	ds_write_b128 v121, v[32:35] offset:34816
	ds_write_b128 v120, v[16:19] offset:4352
	ds_write_b128 v120, v[28:31] offset:21760
	ds_write_b128 v121, v[40:43] offset:39424
	ds_write_b128 v120, v[20:23] offset:8704
	ds_write_b128 v120, v[24:27] offset:26112
	ds_write_b128 v121, v[36:39] offset:44032
	ds_write_b128 v120, v[48:51] offset:13056
	ds_write_b128 v120, v[56:59] offset:30464
	ds_write_b128 v121, v[60:63] offset:48640
	ds_write_b128 v121, v[52:55] offset:53248
	ds_write_b128 v121, v[68:71] offset:57856
	v_add_co_u32_e32 v36, vcc, s5, v130
	s_lshl_b32 s6, s18, 13
	s_nop 0
	v_addc_co_u32_e32 v37, vcc, 0, v131, vcc
	v_add_co_u32_e32 v48, vcc, s5, v132
	v_lshl_add_u64 v[136:137], v[118:119], 0, s[6:7]
	s_nop 0
	v_addc_co_u32_e32 v49, vcc, 0, v133, vcc
	v_add_co_u32_e32 v50, vcc, 0x3000, v128
	global_load_dwordx4 v[0:3], v[128:129], off
	global_load_dwordx4 v[4:7], v[130:131], off
	global_load_dwordx4 v[32:35], v[132:133], off
	v_addc_co_u32_e32 v51, vcc, 0, v129, vcc
	v_add_co_u32_e32 v56, vcc, 0x3000, v130
	global_load_dwordx4 v[16:19], v[134:135], off offset:-4096
	global_load_dwordx4 v[20:23], v[134:135], off
	global_load_dwordx4 v[52:55], v[136:137], off
	v_addc_co_u32_e32 v57, vcc, 0, v131, vcc
	v_add_co_u32_e32 v60, vcc, 0x3000, v132
	global_load_dwordx4 v[28:31], v[36:37], off offset:-4096
	global_load_dwordx4 v[24:27], v[36:37], off
	v_addc_co_u32_e32 v61, vcc, 0, v133, vcc
	v_add_co_u32_e32 v68, vcc, 0x1000, v136
	global_load_dwordx4 v[40:43], v[48:49], off offset:-4096
	global_load_dwordx4 v[36:39], v[48:49], off
	v_addc_co_u32_e32 v69, vcc, 0, v137, vcc
	global_load_dwordx4 v[48:51], v[50:51], off
	s_nop 0
	global_load_dwordx4 v[56:59], v[56:57], off
	s_nop 0
	global_load_dwordx4 v[60:63], v[60:61], off
	s_cmp_gt_u32 s9, 29
	global_load_dwordx4 v[68:71], v[68:69], off
	s_waitcnt lgkmcnt(0)
	s_barrier
	s_cbranch_scc0 .LBB0_599
; #define SC_BAR() do { asm volatile("s_waitcnt lgkmcnt(0)" ::: "memory"); __builtin_amdgcn_s_barrier(); asm volatile("" ::: "memory"); } while (0)
; #define SC_UG(chs) do { const bf16_t* U_ = (const bf16_t*)(p.ws + WS_UT) + (size_t)(chs) * 8192; const float* G_ = (const float*)(p.ws + WS_GB) + (size_t)(chs) * 64; \
;         _Pragma("unroll") for (int tt = 0; tt < 4; ++tt) { u4n[tt] = *(const bf16x4*)(U_ + dv * 64 + 16 * tt + 4 * fq); g4n[tt] = *(const f32x4*)(G_ + 16 * tt + 4 * fq); } \
;         Gln = G_[63]; } while (0)
; template <bool PROMPT>
; __device__ __forceinline__ void scan_block(const Params& p, LAS unsigned char* lds, int chs0, int nsteps, const float* s0, float* sfin, int rowbase, int ntok, int h, int half) {
;     ...
;     bf16_t* CAT = (bf16_t*)(p.ws + WS_CAT);
;     f32x4 ST[8];
; #pragma unroll
;     for (int T = 0; T < 8; ++T)
; #pragma unroll
;         for (int jj = 0; jj < 4; ++jj) ST[T][jj] = s0 ? s0[(size_t)(16 * T + 4 * fq + jj) * 128 + dv] : 0.f;
;     bf16x4 u4n[4]; f32x4 g4n[4]; float Gln;
;     ...
;     SC_UG(chs0);
;     SC_BAR();
.LBB0_600:
	s_andn2_saveexec_b64 s[2:3], s[2:3]
	s_cbranch_execz .LBB0_604
	s_lshl_b32 s1, s33, 6
	s_mov_b32 s5, 0
	s_and_b32 s1, s1, 64
	s_waitcnt vmcnt(0)
	v_lshrrev_b32_e32 v0, 2, v184
	s_lshl_b64 s[6:7], s[4:5], 14
	v_and_b32_e32 v0, 48, v0
	s_add_u32 s10, s50, s6
	v_or3_b32 v160, s1, v0, v128
	s_addc_u32 s11, s51, s7
	s_lshl_b64 s[8:9], s[4:5], 8
	v_bfe_u32 v162, v184, 4, 2
	s_add_u32 s1, s50, s8
	v_mov_b32_e32 v121, 0
	v_lshlrev_b32_e32 v120, 7, v160
	s_addc_u32 s4, s51, s9
	v_lshl_add_u64 v[0:1], s[10:11], 0, v[120:121]
	v_lshlrev_b32_e32 v16, 3, v162
	v_mov_b32_e32 v17, v121
	s_add_u32 s14, s1, 0xd0e8800
	v_lshl_add_u64 v[0:1], v[0:1], 0, v[16:17]
	s_mov_b32 s1, 0xbee8000
	s_addc_u32 s15, s4, 0
	s_mov_b64 s[10:11], 0xbee8800
	v_add_co_u32_e32 v20, vcc, s1, v0
	v_lshlrev_b32_e32 v163, 4, v162
	v_lshl_add_u64 v[18:19], v[0:1], 0, s[10:11]
	v_addc_co_u32_e32 v21, vcc, 0, v1, vcc
	global_load_dwordx4 v[12:15], v163, s[14:15]
	global_load_dwordx4 v[8:11], v163, s[14:15] offset:64
	global_load_dwordx2 v[118:119], v[20:21], off offset:2048
	global_load_dwordx2 v[116:117], v[18:19], off offset:32
	global_load_dwordx2 v[114:115], v[18:19], off offset:64
	global_load_dwordx2 v[112:113], v[18:19], off offset:96
	global_load_dwordx4 v[4:7], v163, s[14:15] offset:128
	global_load_dwordx4 v[0:3], v163, s[14:15] offset:192
	global_load_dword v165, v121, s[14:15] offset:252
	s_movk_i32 s4, 0x110
	v_mov_b32_e32 v17, 0x1100
	v_mad_u32_u24 v168, v128, s4, v17
	v_mov_b32_e32 v17, 0x2200
	v_mad_u32_u24 v167, v128, s4, v17
	v_mov_b32_e32 v17, 0x3300
	v_mad_u32_u24 v166, v128, s4, v17
	s_lshl_b32 s4, s33, 18
	s_lshl_b32 s1, s0, 7
	s_and_b32 s4, s4, 0xe00000
	s_and_b32 s1, s1, 0x180
	v_lshl_or_b32 v17, v162, 12, s4
	v_or3_b32 v17, v17, s1, v160
	v_lshlrev_b32_e32 v17, 1, v17
	v_or_b32_e32 v18, 0x19c00, v17
	v_mov_b32_e32 v19, v121
	s_mov_b64 s[10:11], 0x9b40000
	v_lshl_add_u64 v[122:123], v[18:19], 0, s[10:11]
	v_or_b32_e32 v18, 0x19400, v17
	v_lshl_add_u64 v[124:125], v[18:19], 0, s[10:11]
	v_or_b32_e32 v18, 0x18c00, v17
	v_lshl_add_u64 v[126:127], v[18:19], 0, s[10:11]
	v_or_b32_e32 v18, 0x18400, v17
	v_mul_u32_u24_e32 v169, 0x110, v128
	v_mul_u32_u24_e32 v164, 0x90, v128
	v_lshl_add_u64 v[128:129], v[18:19], 0, s[10:11]
	v_or_b32_e32 v18, 0x11c00, v17
	v_lshl_add_u64 v[130:131], v[18:19], 0, s[10:11]
	v_or_b32_e32 v18, 0x11400, v17
	v_lshl_add_u64 v[132:133], v[18:19], 0, s[10:11]
	v_or_b32_e32 v18, 0x10c00, v17
	v_lshl_add_u64 v[134:135], v[18:19], 0, s[10:11]
	v_or_b32_e32 v18, 0x10400, v17
	v_lshl_add_u64 v[136:137], v[18:19], 0, s[10:11]
	v_or_b32_e32 v18, 0x9c00, v17
	v_lshl_add_u64 v[138:139], v[18:19], 0, s[10:11]
	v_or_b32_e32 v18, 0x9400, v17
	v_lshl_add_u64 v[140:141], v[18:19], 0, s[10:11]
	v_or_b32_e32 v18, 0x8c00, v17
	v_lshl_add_u64 v[142:143], v[18:19], 0, s[10:11]
	v_or_b32_e32 v18, 0x8400, v17
	v_lshl_add_u64 v[144:145], v[18:19], 0, s[10:11]
	v_or_b32_e32 v18, 0x1c00, v17
	v_lshl_add_u64 v[146:147], v[18:19], 0, s[10:11]
	v_or_b32_e32 v18, 0x1400, v17
	s_waitcnt lgkmcnt(0)
	s_barrier
	v_lshl_add_u64 v[148:149], v[18:19], 0, s[10:11]
	v_or_b32_e32 v18, 0xc00, v17
	v_lshl_add_u64 v[150:151], v[18:19], 0, s[10:11]
	v_or_b32_e32 v18, 0x400, v17
	s_add_u32 s4, s8, 0xd0e89fc
	v_or3_b32 v16, s6, v120, v16
	v_mov_b32_e32 v17, s7
	s_mov_b64 s[6:7], 0xbeec840
	v_lshrrev_b32_e32 v161, 4, v184
	v_lshlrev_b32_e32 v170, 2, v162
	v_lshl_add_u64 v[152:153], v[18:19], 0, s[10:11]
	v_or_b32_e32 v154, s8, v163
	v_mov_b32_e32 v155, s9
	s_addc_u32 s14, s9, 0
	v_lshl_add_u64 v[156:157], v[16:17], 0, s[6:7]
	s_mov_b32 s15, 0xd0e8000
	s_mov_b64 s[6:7], 0x20000
	s_mov_b64 s[8:9], 0x100
	s_mov_b64 s[10:11], 0x4000
	v_mov_b32_e32 v32, 0
	v_mov_b32_e32 v33, v121
	v_mov_b32_e32 v34, v121
	v_mov_b32_e32 v35, v121
	v_mov_b32_e32 v36, 0
	v_mov_b32_e32 v37, v121
	v_mov_b32_e32 v38, v121
	v_mov_b32_e32 v39, v121
	v_mov_b32_e32 v40, 0
	v_mov_b32_e32 v41, v121
	v_mov_b32_e32 v42, v121
	v_mov_b32_e32 v43, v121
	v_mov_b32_e32 v44, 0
	v_mov_b32_e32 v45, v121
	v_mov_b32_e32 v46, v121
	v_mov_b32_e32 v47, v121
	v_mov_b32_e32 v16, 0
	v_mov_b32_e32 v17, v121
	v_mov_b32_e32 v18, v121
	v_mov_b32_e32 v20, 0
	v_mov_b32_e32 v21, v121
	v_mov_b32_e32 v22, v121
	v_mov_b32_e32 v23, v121
	v_mov_b32_e32 v24, 0
	v_mov_b32_e32 v25, v121
	v_mov_b32_e32 v26, v121
	v_mov_b32_e32 v27, v121
	v_mov_b32_e32 v28, 0
	v_mov_b32_e32 v29, v121
	v_mov_b32_e32 v30, v121
	v_mov_b32_e32 v31, v121
	s_waitcnt vmcnt(0)
	s_branch .Lsc_body
.LBB0_602:
	s_waitcnt vmcnt(16)
; #define LAS __attribute__((address_space(3)))
; __device__ __forceinline__ f32x4 mfma16(const bf16x8& a, const bf16x8& b, const f32x4& c) { return __builtin_amdgcn_mfma_f32_16x16x32_bf16(a, b, c, 0, 0, 0); }
; #define SC_UG(chs) do { const bf16_t* U_ = (const bf16_t*)(p.ws + WS_UT) + (size_t)(chs) * 8192; const float* G_ = (const float*)(p.ws + WS_GB) + (size_t)(chs) * 64; \
;         _Pragma("unroll") for (int tt = 0; tt < 4; ++tt) { u4n[tt] = *(const bf16x4*)(U_ + dv * 64 + 16 * tt + 4 * fq); g4n[tt] = *(const f32x4*)(G_ + 16 * tt + 4 * fq); } \
;         Gln = G_[63]; } while (0)
; template <bool PROMPT>
; __device__ __forceinline__ void scan_block(const Params& p, LAS unsigned char* lds, int chs0, int nsteps, const float* s0, float* sfin, int rowbase, int ntok, int h, int half) {
;     ...
;     for (int n = 0; n < nsteps; ++n) {
;         bf16x4 u4[4]; f32x4 g4[4]; const float Glc = Gln;
; #pragma unroll
;         for (int tt = 0; tt < 4; ++tt) { u4[tt] = u4n[tt]; g4[tt] = g4n[tt]; }
;         if constexpr (PROMPT) { const int c = (n + 1 < nsteps) ? n + 1 : nsteps - 1; SC_UG(chs0 + c); }
;         __builtin_amdgcn_sched_barrier(0);
;         const LAS unsigned char* B = lds + (n & 1) * SC_BUF;
;         bf16x8 Sb[4];
; #pragma unroll
;         for (int P = 0; P < 4; ++P) Sb[P] = pack8(ST[2 * P], ST[2 * P + 1]);
;         f32x4 ws[4], qs[4];
;         bf16x8 fa[8];
; #pragma unroll
;         for (int tt = 0; tt < 4; ++tt) {
; #pragma unroll
;             for (int P = 0; P < 4; ++P) { fa[P] = *(const LAS bf16x8*)(B + SC_W + (16 * tt + fr) * 272 + (32 * P + 8 * fq) * 2);
;                                           fa[4 + P] = *(const LAS bf16x8*)(B + SC_QS + (16 * tt + fr) * 272 + (32 * P + 8 * fq) * 2); }
;             __builtin_amdgcn_sched_barrier(0);
;             ws[tt] = (f32x4){0.f, 0.f, 0.f, 0.f}; qs[tt] = (f32x4){0.f, 0.f, 0.f, 0.f};
; #pragma unroll
;             for (int P = 0; P < 4; ++P) { ws[tt] = mfma16(fa[P], Sb[P], ws[tt]); qs[tt] = mfma16(fa[4 + P], Sb[P], qs[tt]); }
;             __builtin_amdgcn_sched_barrier(0);
;         }
.Lsc_body:
	v_mov_b64_e32 v[50:51], v[2:3]
	v_mov_b64_e32 v[48:49], v[0:1]
	v_lshl_add_u64 v[2:3], s[50:51], 0, v[154:155]
	v_add_co_u32_e32 v2, vcc, s15, v2
	v_mov_b64_e32 v[62:63], v[14:15]
	v_mov_b64_e32 v[58:59], v[10:11]
	v_mov_b64_e32 v[54:55], v[6:7]
	s_add_i32 s16, s5, 1
	v_lshl_add_u64 v[0:1], s[50:51], 0, v[156:157]
	v_addc_co_u32_e32 v3, vcc, 0, v3, vcc
	v_mov_b64_e32 v[60:61], v[12:13]
	v_mov_b64_e32 v[56:57], v[8:9]
	v_mov_b64_e32 v[52:53], v[4:5]
	v_mov_b64_e32 v[202:203], v[118:119]
	v_mov_b64_e32 v[158:159], v[116:117]
	v_mov_b64_e32 v[66:67], v[114:115]
	v_mov_b64_e32 v[64:65], v[112:113]
	global_load_dwordx2 v[118:119], v[0:1], off offset:-64
	global_load_dwordx2 v[116:117], v[0:1], off offset:-32
	global_load_dwordx2 v[114:115], v[0:1], off
	global_load_dwordx2 v[112:113], v[0:1], off offset:32
	s_add_u32 s18, s50, s4
	global_load_dwordx4 v[12:15], v[2:3], off offset:2304
	global_load_dwordx4 v[8:11], v[2:3], off offset:2368
	global_load_dwordx4 v[4:7], v[2:3], off offset:2432
	s_nop 0
	global_load_dwordx4 v[0:3], v[2:3], off offset:2496
	s_addc_u32 s19, s51, s14
	v_mov_b32_e32 v120, v165
	global_load_dword v165, v121, s[18:19]
	s_bitcmp1_b32 s5, 0
	s_cselect_b32 s5, 0xf400, 0
	s_add_i32 s5, s5, 0
	v_add_u32_e32 v171, s5, v163
	v_add_u32_e32 v108, v171, v169
	ds_read_b128 v[80:83], v108
	ds_read_b128 v[84:87], v108 offset:64
	ds_read_b128 v[88:91], v108 offset:17408
	ds_read_b128 v[92:95], v108 offset:17472
	ds_read_b128 v[96:99], v108 offset:128
	ds_read_b128 v[100:103], v108 offset:192
	ds_read_b128 v[104:107], v108 offset:17536
	ds_read_b128 v[108:111], v108 offset:17600
	v_cvt_pk_bf16_f32 v68, v28, v29
	v_cvt_pk_bf16_f32 v69, v30, v31
	v_cvt_pk_bf16_f32 v70, v24, v25
	v_cvt_pk_bf16_f32 v71, v26, v27
	v_cvt_pk_bf16_f32 v72, v20, v21
	v_cvt_pk_bf16_f32 v73, v22, v23
	v_cvt_pk_bf16_f32 v74, v16, v17
	v_cvt_pk_bf16_f32 v75, v18, v19
	v_cvt_pk_bf16_f32 v76, v44, v45
	v_cvt_pk_bf16_f32 v77, v46, v47
	v_cvt_pk_bf16_f32 v78, v40, v41
	v_cvt_pk_bf16_f32 v79, v42, v43
	v_cvt_pk_bf16_f32 v172, v36, v37
	v_cvt_pk_bf16_f32 v173, v38, v39
	v_cvt_pk_bf16_f32 v174, v32, v33
	v_cvt_pk_bf16_f32 v175, v34, v35
	s_waitcnt lgkmcnt(0)
	v_mfma_f32_16x16x32_bf16 v[80:83], v[80:83], v[68:71], 0
	v_mfma_f32_16x16x32_bf16 v[88:91], v[88:91], v[68:71], 0
	v_mfma_f32_16x16x32_bf16 v[80:83], v[84:87], v[72:75], v[80:83]
	v_mfma_f32_16x16x32_bf16 v[84:87], v[92:95], v[72:75], v[88:91]
	v_mfma_f32_16x16x32_bf16 v[80:83], v[96:99], v[76:79], v[80:83]
	v_mfma_f32_16x16x32_bf16 v[84:87], v[104:107], v[76:79], v[84:87]
	v_mfma_f32_16x16x32_bf16 v[176:179], v[100:103], v[172:175], v[80:83]
	v_mfma_f32_16x16x32_bf16 v[104:107], v[108:111], v[172:175], v[84:87]
	v_add_u32_e32 v180, v171, v168
	s_nop 3
	ds_read_b128 v[80:83], v180
	ds_read_b128 v[84:87], v180 offset:64
	ds_read_b128 v[88:91], v180 offset:17408
	ds_read_b128 v[92:95], v180 offset:17472
	ds_read_b128 v[96:99], v180 offset:128
	ds_read_b128 v[100:103], v180 offset:192
	ds_read_b128 v[108:111], v180 offset:17536
	ds_read_b128 v[180:183], v180 offset:17600
	s_waitcnt lgkmcnt(7)
	v_mfma_f32_16x16x32_bf16 v[80:83], v[80:83], v[68:71], 0
	s_waitcnt lgkmcnt(5)
	v_mfma_f32_16x16x32_bf16 v[88:91], v[88:91], v[68:71], 0
	v_mfma_f32_16x16x32_bf16 v[80:83], v[84:87], v[72:75], v[80:83]
	s_waitcnt lgkmcnt(4)
	v_mfma_f32_16x16x32_bf16 v[84:87], v[92:95], v[72:75], v[88:91]
	s_waitcnt lgkmcnt(3)
	v_mfma_f32_16x16x32_bf16 v[80:83], v[96:99], v[76:79], v[80:83]
	s_waitcnt lgkmcnt(1)
	v_mfma_f32_16x16x32_bf16 v[84:87], v[108:111], v[76:79], v[84:87]
	v_mfma_f32_16x16x32_bf16 v[186:189], v[100:103], v[172:175], v[80:83]
	s_waitcnt lgkmcnt(0)
	v_mfma_f32_16x16x32_bf16 v[180:183], v[180:183], v[172:175], v[84:87]
	v_add_u32_e32 v185, v171, v167
	s_nop 1
	ds_read_b128 v[80:83], v185
	s_nop 0
	ds_read_b128 v[84:87], v185 offset:64
	ds_read_b128 v[88:91], v185 offset:17408
	ds_read_b128 v[92:95], v185 offset:17472
	ds_read_b128 v[96:99], v185 offset:128
	ds_read_b128 v[100:103], v185 offset:192
	ds_read_b128 v[108:111], v185 offset:17536
	ds_read_b128 v[190:193], v185 offset:17600
	s_waitcnt lgkmcnt(7)
	v_mfma_f32_16x16x32_bf16 v[80:83], v[80:83], v[68:71], 0
	s_waitcnt lgkmcnt(5)
	v_mfma_f32_16x16x32_bf16 v[88:91], v[88:91], v[68:71], 0
	v_mfma_f32_16x16x32_bf16 v[80:83], v[84:87], v[72:75], v[80:83]
	s_waitcnt lgkmcnt(4)
	v_mfma_f32_16x16x32_bf16 v[84:87], v[92:95], v[72:75], v[88:91]
	s_waitcnt lgkmcnt(3)
	v_mfma_f32_16x16x32_bf16 v[80:83], v[96:99], v[76:79], v[80:83]
	s_waitcnt lgkmcnt(1)
	v_mfma_f32_16x16x32_bf16 v[84:87], v[108:111], v[76:79], v[84:87]
	v_mfma_f32_16x16x32_bf16 v[194:197], v[100:103], v[172:175], v[80:83]
	s_waitcnt lgkmcnt(0)
	v_mfma_f32_16x16x32_bf16 v[100:103], v[190:193], v[172:175], v[84:87]
	v_add_u32_e32 v185, v171, v166
	s_nop 1
	ds_read_b128 v[80:83], v185
	s_nop 0
	ds_read_b128 v[84:87], v185 offset:64
	ds_read_b128 v[88:91], v185 offset:17408
	ds_read_b128 v[92:95], v185 offset:17472
	ds_read_b128 v[96:99], v185 offset:128
	ds_read_b128 v[108:111], v185 offset:192
	ds_read_b128 v[190:193], v185 offset:17536
	ds_read_b128 v[198:201], v185 offset:17600
	s_waitcnt lgkmcnt(7)
	v_mfma_f32_16x16x32_bf16 v[80:83], v[80:83], v[68:71], 0
	s_waitcnt lgkmcnt(5)
	v_mfma_f32_16x16x32_bf16 v[68:71], v[88:91], v[68:71], 0
	v_mfma_f32_16x16x32_bf16 v[80:83], v[84:87], v[72:75], v[80:83]
	s_waitcnt lgkmcnt(4)
	v_mfma_f32_16x16x32_bf16 v[68:71], v[92:95], v[72:75], v[68:71]
	s_waitcnt lgkmcnt(3)
	v_mfma_f32_16x16x32_bf16 v[72:75], v[96:99], v[76:79], v[80:83]
	s_waitcnt lgkmcnt(1)
	v_mfma_f32_16x16x32_bf16 v[68:71], v[190:193], v[76:79], v[68:71]
	v_mfma_f32_16x16x32_bf16 v[190:193], v[108:111], v[172:175], v[72:75]
	s_waitcnt lgkmcnt(0)
; #define LAS __attribute__((address_space(3)))
; __device__ __forceinline__ float bf2f(short b) { return __uint_as_float(((unsigned)(unsigned short)b) << 16); }
; template <bool PROMPT>
; __device__ __forceinline__ void scan_block(const Params& p, LAS unsigned char* lds, int chs0, int nsteps, const float* s0, float* sfin, int rowbase, int ntok, int h, int half) {
;     ...
;         bf16x8 fq_[8], fk[8];
; #pragma unroll
;         for (int tt = 0; tt < 4; ++tt)
; #pragma unroll
;             for (int u = 0; u < 2; ++u) fq_[tt * 2 + u] = *(const LAS bf16x8*)(B + SC_QK + (16 * tt + fr) * 144 + (32 * u + 8 * fq) * 2);
;         __builtin_amdgcn_sched_barrier(0);
;         f32x4 vn[4], vd[4];
; #pragma unroll
;         for (int tt = 0; tt < 4; ++tt)
; #pragma unroll
;             for (int jj = 0; jj < 4; ++jj) { vn[tt][jj] = bf2f(u4[tt][jj]) - ws[tt][jj]; vd[tt][jj] = vn[tt][jj] * __expf(Glc - g4[tt][jj]); }
;         bf16x8 Vb[2], Vd[2];
; #pragma unroll
;         for (int u = 0; u < 2; ++u) { Vb[u] = pack8(vn[2 * u], vn[2 * u + 1]); Vd[u] = pack8(vd[2 * u], vd[2 * u + 1]); }
;         f32x4 o[4];
; #pragma unroll
;         for (int tt = 0; tt < 4; ++tt)
; #pragma unroll
;             for (int jj = 0; jj < 4; ++jj) o[tt][jj] = qs[tt][jj] * __expf(g4[tt][jj]);
;         const float gt = __expf(Glc);
; #pragma unroll
;         for (int T = 0; T < 8; ++T) ST[T] = ST[T] * gt;
;         __builtin_amdgcn_sched_barrier(0);
; #pragma unroll
;         for (int T = 0; T < 4; ++T)
; #pragma unroll
;             for (int u = 0; u < 2; ++u) fk[T * 2 + u] = *(const LAS bf16x8*)(B + SC_KT + (16 * T + fr) * 144 + (32 * u + 8 * fq) * 2);
	v_mfma_f32_16x16x32_bf16 v[108:111], v[198:201], v[172:175], v[68:71]
	v_add_u32_e32 v171, v171, v164
	s_nop 3
	ds_read_b128 v[68:71], v171 offset:53248
	ds_read_b128 v[72:75], v171 offset:53312
	ds_read_b128 v[76:79], v171 offset:55552
	ds_read_b128 v[80:83], v171 offset:55616
	ds_read_b128 v[84:87], v171 offset:57856
	ds_read_b128 v[88:91], v171 offset:57920
	ds_read_b128 v[92:95], v171 offset:60160
	ds_read_b128 v[96:99], v171 offset:60224
	v_sub_f32_e32 v172, v120, v60
	v_sub_f32_e32 v173, v120, v61
	v_mul_f32_e32 v172, 0x3fb8aa3b, v172
	v_mul_f32_e32 v173, 0x3fb8aa3b, v173
	v_exp_f32_e32 v172, v172
	v_exp_f32_e32 v173, v173
	v_and_b32_e32 v175, 0xffff0000, v202
	v_lshlrev_b32_e32 v174, 16, v202
	v_pk_add_f32 v[174:175], v[174:175], v[176:177] neg_lo:[0,1] neg_hi:[0,1]
	v_and_b32_e32 v199, 0xffff0000, v203
	v_pk_mul_f32 v[176:177], v[172:173], v[174:175]
	v_sub_f32_e32 v172, v120, v62
	v_sub_f32_e32 v173, v120, v63
	v_mul_f32_e32 v172, 0x3fb8aa3b, v172
	v_mul_f32_e32 v173, 0x3fb8aa3b, v173
	v_exp_f32_e32 v172, v172
	v_exp_f32_e32 v173, v173
	v_lshlrev_b32_e32 v198, 16, v203
	v_pk_add_f32 v[178:179], v[198:199], v[178:179] neg_lo:[0,1] neg_hi:[0,1]
	v_and_b32_e32 v201, 0xffff0000, v158
	v_pk_mul_f32 v[198:199], v[172:173], v[178:179]
	v_sub_f32_e32 v172, v120, v56
	v_sub_f32_e32 v173, v120, v57
	v_mul_f32_e32 v172, 0x3fb8aa3b, v172
	v_mul_f32_e32 v173, 0x3fb8aa3b, v173
	v_exp_f32_e32 v172, v172
	v_exp_f32_e32 v173, v173
	v_lshlrev_b32_e32 v200, 16, v158
	v_sub_f32_e32 v158, v120, v58
	v_pk_add_f32 v[186:187], v[200:201], v[186:187] neg_lo:[0,1] neg_hi:[0,1]
	v_mul_f32_e32 v158, 0x3fb8aa3b, v158
	v_pk_mul_f32 v[200:201], v[172:173], v[186:187]
	v_exp_f32_e32 v172, v158
	v_sub_f32_e32 v158, v120, v59
	v_mul_f32_e32 v158, 0x3fb8aa3b, v158
	v_exp_f32_e32 v173, v158
	v_and_b32_e32 v203, 0xffff0000, v159
	v_lshlrev_b32_e32 v202, 16, v159
	v_pk_add_f32 v[158:159], v[202:203], v[188:189] neg_lo:[0,1] neg_hi:[0,1]
	v_and_b32_e32 v203, 0xffff0000, v66
	v_pk_mul_f32 v[188:189], v[172:173], v[158:159]
	v_sub_f32_e32 v172, v120, v52
	v_sub_f32_e32 v173, v120, v53
	v_mul_f32_e32 v172, 0x3fb8aa3b, v172
	v_mul_f32_e32 v173, 0x3fb8aa3b, v173
	v_exp_f32_e32 v172, v172
	v_exp_f32_e32 v173, v173
	v_lshlrev_b32_e32 v202, 16, v66
	v_sub_f32_e32 v66, v120, v54
	v_pk_add_f32 v[194:195], v[202:203], v[194:195] neg_lo:[0,1] neg_hi:[0,1]
	v_mul_f32_e32 v66, 0x3fb8aa3b, v66
	v_pk_mul_f32 v[202:203], v[172:173], v[194:195]
	v_exp_f32_e32 v172, v66
	v_sub_f32_e32 v66, v120, v55
	v_mul_f32_e32 v66, 0x3fb8aa3b, v66
	v_exp_f32_e32 v173, v66
	v_and_b32_e32 v205, 0xffff0000, v67
	v_lshlrev_b32_e32 v204, 16, v67
	v_pk_add_f32 v[66:67], v[204:205], v[196:197] neg_lo:[0,1] neg_hi:[0,1]
	v_and_b32_e32 v205, 0xffff0000, v64
	v_pk_mul_f32 v[196:197], v[172:173], v[66:67]
	v_sub_f32_e32 v172, v120, v48
	v_sub_f32_e32 v173, v120, v49
	v_mul_f32_e32 v172, 0x3fb8aa3b, v172
	v_mul_f32_e32 v173, 0x3fb8aa3b, v173
	v_exp_f32_e32 v172, v172
	v_exp_f32_e32 v173, v173
	v_lshlrev_b32_e32 v204, 16, v64
	v_sub_f32_e32 v64, v120, v50
	v_pk_add_f32 v[190:191], v[204:205], v[190:191] neg_lo:[0,1] neg_hi:[0,1]
	v_mul_f32_e32 v64, 0x3fb8aa3b, v64
	v_pk_mul_f32 v[204:205], v[172:173], v[190:191]
	v_exp_f32_e32 v172, v64
	v_sub_f32_e32 v64, v120, v51
	v_mul_f32_e32 v64, 0x3fb8aa3b, v64
	v_exp_f32_e32 v173, v64
	v_mul_f32_e32 v60, 0x3fb8aa3b, v60
	v_mul_f32_e32 v61, 0x3fb8aa3b, v61
	v_and_b32_e32 v207, 0xffff0000, v65
	v_lshlrev_b32_e32 v206, 16, v65
	v_exp_f32_e32 v60, v60
	v_exp_f32_e32 v61, v61
	v_mul_f32_e32 v54, 0x3fb8aa3b, v54
	v_mul_f32_e32 v55, 0x3fb8aa3b, v55
	v_pk_add_f32 v[64:65], v[206:207], v[192:193] neg_lo:[0,1] neg_hi:[0,1]
	v_mul_f32_e32 v56, 0x3fb8aa3b, v56
	v_exp_f32_e32 v54, v54
	v_exp_f32_e32 v55, v55
	v_pk_mul_f32 v[192:193], v[172:173], v[64:65]
	v_cvt_pk_bf16_f32 v172, v174, v175
	v_cvt_pk_bf16_f32 v175, v158, v159
	v_mul_f32_e32 v62, 0x3fb8aa3b, v62
	v_mul_f32_e32 v63, 0x3fb8aa3b, v63
	v_exp_f32_e32 v158, v56
	v_mul_f32_e32 v56, 0x3fb8aa3b, v57
	v_mul_f32_e32 v57, 0x3fb8aa3b, v58
	v_cvt_pk_bf16_f32 v173, v178, v179
	v_cvt_pk_bf16_f32 v179, v188, v189
	v_cvt_pk_bf16_f32 v188, v190, v191
	v_exp_f32_e32 v62, v62
	v_exp_f32_e32 v63, v63
	v_exp_f32_e32 v190, v57
	v_mul_f32_e32 v57, 0x3fb8aa3b, v59
	v_mul_f32_e32 v52, 0x3fb8aa3b, v52
	v_exp_f32_e32 v191, v57
	v_exp_f32_e32 v159, v56
	v_pk_mul_f32 v[56:57], v[60:61], v[104:105]
	v_exp_f32_e32 v104, v52
	v_mul_f32_e32 v52, 0x3fb8aa3b, v53
	v_mul_f32_e32 v50, 0x3fb8aa3b, v50
	v_exp_f32_e32 v105, v52
	v_pk_mul_f32 v[52:53], v[54:55], v[102:103]
	v_exp_f32_e32 v54, v50
	v_mul_f32_e32 v50, 0x3fb8aa3b, v51
	v_exp_f32_e32 v55, v50
	v_mul_f32_e32 v50, 0x3fb8aa3b, v120
	v_pk_mul_f32 v[58:59], v[62:63], v[106:107]
	v_mul_f32_e32 v48, 0x3fb8aa3b, v48
	v_mul_f32_e32 v49, 0x3fb8aa3b, v49
	v_exp_f32_e32 v106, v50
	v_exp_f32_e32 v48, v48
	v_exp_f32_e32 v49, v49
	v_cvt_pk_bf16_f32 v174, v186, v187
	v_pk_mul_f32 v[30:31], v[30:31], v[106:107] op_sel_hi:[1,0]
	v_pk_mul_f32 v[28:29], v[28:29], v[106:107] op_sel_hi:[1,0]
	v_pk_mul_f32 v[26:27], v[26:27], v[106:107] op_sel_hi:[1,0]
	v_pk_mul_f32 v[24:25], v[24:25], v[106:107] op_sel_hi:[1,0]
	v_pk_mul_f32 v[22:23], v[22:23], v[106:107] op_sel_hi:[1,0]
	v_pk_mul_f32 v[20:21], v[20:21], v[106:107] op_sel_hi:[1,0]
	v_pk_mul_f32 v[18:19], v[18:19], v[106:107] op_sel_hi:[1,0]
	v_pk_mul_f32 v[16:17], v[16:17], v[106:107] op_sel_hi:[1,0]
	v_pk_mul_f32 v[46:47], v[46:47], v[106:107] op_sel_hi:[1,0]
	v_pk_mul_f32 v[44:45], v[44:45], v[106:107] op_sel_hi:[1,0]
	v_pk_mul_f32 v[42:43], v[42:43], v[106:107] op_sel_hi:[1,0]
	v_pk_mul_f32 v[40:41], v[40:41], v[106:107] op_sel_hi:[1,0]
	v_pk_mul_f32 v[38:39], v[38:39], v[106:107] op_sel_hi:[1,0]
	v_pk_mul_f32 v[36:37], v[36:37], v[106:107] op_sel_hi:[1,0]
	v_pk_mul_f32 v[34:35], v[34:35], v[106:107] op_sel_hi:[1,0]
	v_pk_mul_f32 v[32:33], v[32:33], v[106:107] op_sel_hi:[1,0]
	v_cvt_pk_bf16_f32 v176, v176, v177
	v_cvt_pk_bf16_f32 v177, v198, v199
	v_cvt_pk_bf16_f32 v178, v200, v201
	v_cvt_pk_bf16_f32 v186, v194, v195
	v_cvt_pk_bf16_f32 v187, v66, v67
	v_cvt_pk_bf16_f32 v189, v64, v65
	v_cvt_pk_bf16_f32 v64, v202, v203
	v_cvt_pk_bf16_f32 v65, v196, v197
	v_cvt_pk_bf16_f32 v66, v204, v205
	v_cvt_pk_bf16_f32 v67, v192, v193
	v_pk_mul_f32 v[62:63], v[190:191], v[182:183]
	v_pk_mul_f32 v[60:61], v[158:159], v[180:181]
	v_pk_mul_f32 v[50:51], v[104:105], v[100:101]
	v_pk_mul_f32 v[102:103], v[54:55], v[110:111]
	v_pk_mul_f32 v[100:101], v[48:49], v[108:109]
	ds_read_b128 v[104:107], v171 offset:34816
	ds_read_b128 v[108:111], v171 offset:34880
	ds_read_b128 v[180:183], v171 offset:37120
	ds_read_b128 v[190:193], v171 offset:37184
	ds_read_b128 v[194:197], v171 offset:39424
	ds_read_b128 v[198:201], v171 offset:39488
	ds_read_b128 v[202:205], v171 offset:41728
	ds_read_b128 v[206:209], v171 offset:41792
	s_waitcnt lgkmcnt(14)
; #define LAS __attribute__((address_space(3)))
; __device__ __forceinline__ bf16_t f2bf(float f) { return (bf16_t)(cvt_pk_bf16(f, 0.f) & 0xffffu); }
; __device__ __forceinline__ f32x4 mfma16(const bf16x8& a, const bf16x8& b, const f32x4& c) { return __builtin_amdgcn_mfma_f32_16x16x32_bf16(a, b, c, 0, 0, 0); }
; #define SC_BAR() do { asm volatile("s_waitcnt lgkmcnt(0)" ::: "memory"); __builtin_amdgcn_s_barrier(); asm volatile("" ::: "memory"); } while (0)
; template <bool PROMPT>
; __device__ __forceinline__ void scan_block(const Params& p, LAS unsigned char* lds, int chs0, int nsteps, const float* s0, float* sfin, int rowbase, int ntok, int h, int half) {
;     ...
; #pragma unroll
;         for (int tt = 0; tt < 4; ++tt)
; #pragma unroll
;             for (int u = 0; u < 2; ++u) o[tt] = mfma16(fq_[tt * 2 + u], Vb[u], o[tt]);
;         __builtin_amdgcn_sched_barrier(0);
; #pragma unroll
;         for (int T = 0; T < 4; ++T)
; #pragma unroll
;             for (int u = 0; u < 2; ++u) fq_[T * 2 + u] = *(const LAS bf16x8*)(B + SC_KT + (16 * (4 + T) + fr) * 144 + (32 * u + 8 * fq) * 2);
;         __builtin_amdgcn_sched_barrier(0);
; #pragma unroll
;         for (int T = 0; T < 4; ++T)
; #pragma unroll
;             for (int u = 0; u < 2; ++u) ST[T] = mfma16(fk[T * 2 + u], Vd[u], ST[T]);
;         __builtin_amdgcn_sched_barrier(0);
; #pragma unroll
;         for (int T = 0; T < 4; ++T)
; #pragma unroll
;             for (int u = 0; u < 2; ++u) ST[4 + T] = mfma16(fq_[T * 2 + u], Vd[u], ST[4 + T]);
; #pragma unroll
;         for (int tt = 0; tt < 4; ++tt)
; #pragma unroll
;             for (int jj = 0; jj < 4; ++jj) {
;                 const int tok = 16 * tt + 4 * fq + jj;
;                 if constexpr (PROMPT) {
;                     const unsigned row = (unsigned)(rowbase + n * 64 + tok);
;                     CAT[row * (unsigned)DM + (unsigned)(512 + h * 128 + dv)] = f2bf(o[tt][jj]);
;                 } else {
;                     const unsigned row = (unsigned)(rowbase + n * 64 + (tok < ntok ? tok : 0));
;                     if (tok < ntok) CAT[row * (unsigned)DM + (unsigned)(512 + h * 128 + dv)] = f2bf(o[tt][jj]);
;                 }
;             }
;         SC_BAR();
	v_mfma_f32_16x16x32_bf16 v[54:57], v[68:71], v[172:175], v[56:59]
	s_waitcnt lgkmcnt(13)
	v_mfma_f32_16x16x32_bf16 v[58:61], v[76:79], v[172:175], v[60:63]
	s_waitcnt lgkmcnt(11)
	v_mfma_f32_16x16x32_bf16 v[48:51], v[84:87], v[172:175], v[50:53]
	s_waitcnt lgkmcnt(9)
	v_mfma_f32_16x16x32_bf16 v[68:71], v[92:95], v[172:175], v[100:103]
	v_mfma_f32_16x16x32_bf16 v[54:57], v[72:75], v[186:189], v[54:57]
	v_mfma_f32_16x16x32_bf16 v[58:61], v[80:83], v[186:189], v[58:61]
	v_mfma_f32_16x16x32_bf16 v[48:51], v[88:91], v[186:189], v[48:51]
	s_waitcnt lgkmcnt(8)
	v_mfma_f32_16x16x32_bf16 v[68:71], v[96:99], v[186:189], v[68:71]
	ds_read_b128 v[72:75], v171 offset:44032
	ds_read_b128 v[76:79], v171 offset:44096
	ds_read_b128 v[80:83], v171 offset:46336
	ds_read_b128 v[84:87], v171 offset:46400
	ds_read_b128 v[88:91], v171 offset:48640
	ds_read_b128 v[92:95], v171 offset:48704
	ds_read_b128 v[96:99], v171 offset:50944
	ds_read_b128 v[100:103], v171 offset:51008
	s_waitcnt lgkmcnt(14)
	v_mfma_f32_16x16x32_bf16 v[28:31], v[104:107], v[176:179], v[28:31]
	s_waitcnt lgkmcnt(13)
	v_mfma_f32_16x16x32_bf16 v[24:27], v[180:183], v[176:179], v[24:27]
	s_waitcnt lgkmcnt(11)
	v_mfma_f32_16x16x32_bf16 v[20:23], v[194:197], v[176:179], v[20:23]
	s_waitcnt lgkmcnt(9)
	v_mfma_f32_16x16x32_bf16 v[16:19], v[202:205], v[176:179], v[16:19]
	v_mfma_f32_16x16x32_bf16 v[28:31], v[108:111], v[64:67], v[28:31]
	v_mfma_f32_16x16x32_bf16 v[24:27], v[190:193], v[64:67], v[24:27]
	v_mfma_f32_16x16x32_bf16 v[20:23], v[198:201], v[64:67], v[20:23]
	s_waitcnt lgkmcnt(8)
	v_mfma_f32_16x16x32_bf16 v[16:19], v[206:209], v[64:67], v[16:19]
	s_waitcnt lgkmcnt(7)
	v_mfma_f32_16x16x32_bf16 v[44:47], v[72:75], v[176:179], v[44:47]
	v_cvt_pk_bf16_f32 v104, v54, s0
	v_lshl_add_u64 v[52:53], s[50:51], 0, v[152:153]
	v_cvt_pk_bf16_f32 v110, v50, s0
	s_waitcnt lgkmcnt(5)
	v_mfma_f32_16x16x32_bf16 v[40:43], v[80:83], v[176:179], v[40:43]
	v_lshl_add_u64 v[82:83], s[50:51], 0, v[132:133]
	v_cvt_pk_bf16_f32 v120, v68, s0
	v_cvt_pk_bf16_f32 v158, v69, s0
	s_waitcnt lgkmcnt(3)
	v_mfma_f32_16x16x32_bf16 v[36:39], v[88:91], v[176:179], v[36:39]
	v_lshl_add_u64 v[68:69], s[50:51], 0, v[126:127]
	v_cvt_pk_bf16_f32 v105, v55, s0
	v_lshl_add_u64 v[54:55], s[50:51], 0, v[150:151]
	s_waitcnt lgkmcnt(1)
	v_mfma_f32_16x16x32_bf16 v[32:35], v[96:99], v[176:179], v[32:35]
	v_cvt_pk_bf16_f32 v106, v56, s0
	v_lshl_add_u64 v[62:63], s[50:51], 0, v[148:149]
	v_cvt_pk_bf16_f32 v107, v57, s0
	v_lshl_add_u64 v[56:57], s[50:51], 0, v[146:147]
	v_cvt_pk_bf16_f32 v108, v58, s0
	v_lshl_add_u64 v[72:73], s[50:51], 0, v[144:145]
	v_cvt_pk_bf16_f32 v109, v59, s0
	v_lshl_add_u64 v[58:59], s[50:51], 0, v[142:143]
	v_cvt_pk_bf16_f32 v96, v60, s0
	v_lshl_add_u64 v[74:75], s[50:51], 0, v[140:141]
	v_cvt_pk_bf16_f32 v97, v61, s0
	v_lshl_add_u64 v[60:61], s[50:51], 0, v[138:139]
	v_cvt_pk_bf16_f32 v98, v48, s0
	v_lshl_add_u64 v[80:81], s[50:51], 0, v[136:137]
	v_cvt_pk_bf16_f32 v99, v49, s0
	v_lshl_add_u64 v[48:49], s[50:51], 0, v[134:135]
	v_cvt_pk_bf16_f32 v111, v51, s0
	v_lshl_add_u64 v[50:51], s[50:51], 0, v[130:131]
	v_lshl_add_u64 v[88:89], s[50:51], 0, v[128:129]
	v_cvt_pk_bf16_f32 v159, v70, s0
	v_lshl_add_u64 v[90:91], s[50:51], 0, v[124:125]
	v_cvt_pk_bf16_f32 v171, v71, s0
	v_lshl_add_u64 v[70:71], s[50:51], 0, v[122:123]
	global_store_short v[52:53], v104, off
	global_store_short v[54:55], v105, off
	global_store_short v[62:63], v106, off
	global_store_short v[56:57], v107, off
	global_store_short v[72:73], v108, off
	global_store_short v[58:59], v109, off
	global_store_short v[74:75], v96, off
	global_store_short v[60:61], v97, off
	global_store_short v[80:81], v98, off
	global_store_short v[48:49], v99, off
	v_mfma_f32_16x16x32_bf16 v[44:47], v[76:79], v[64:67], v[44:47]
	global_store_short v[82:83], v110, off
	global_store_short v[50:51], v111, off
	global_store_short v[88:89], v120, off
	global_store_short v[68:69], v158, off
	global_store_short v[90:91], v159, off
	global_store_short v[70:71], v171, off
	s_add_u32 s4, s4, 0x100
	v_mfma_f32_16x16x32_bf16 v[40:43], v[84:87], v[64:67], v[40:43]
	s_waitcnt lgkmcnt(0)
	s_barrier
	v_mfma_f32_16x16x32_bf16 v[36:39], v[92:95], v[64:67], v[36:39]
	s_addc_u32 s14, s14, 0
	v_lshl_add_u64 v[122:123], v[122:123], 0, s[6:7]
	v_lshl_add_u64 v[124:125], v[124:125], 0, s[6:7]
	s_waitcnt lgkmcnt(0)
	v_mfma_f32_16x16x32_bf16 v[32:35], v[100:103], v[64:67], v[32:35]
	v_lshl_add_u64 v[126:127], v[126:127], 0, s[6:7]
	v_lshl_add_u64 v[128:129], v[128:129], 0, s[6:7]
	v_lshl_add_u64 v[130:131], v[130:131], 0, s[6:7]
	v_lshl_add_u64 v[132:133], v[132:133], 0, s[6:7]
	v_lshl_add_u64 v[134:135], v[134:135], 0, s[6:7]
	v_lshl_add_u64 v[136:137], v[136:137], 0, s[6:7]
	v_lshl_add_u64 v[138:139], v[138:139], 0, s[6:7]
	v_lshl_add_u64 v[140:141], v[140:141], 0, s[6:7]
	v_lshl_add_u64 v[142:143], v[142:143], 0, s[6:7]
	v_lshl_add_u64 v[144:145], v[144:145], 0, s[6:7]
	v_lshl_add_u64 v[146:147], v[146:147], 0, s[6:7]
	v_lshl_add_u64 v[148:149], v[148:149], 0, s[6:7]
	v_lshl_add_u64 v[150:151], v[150:151], 0, s[6:7]
	v_lshl_add_u64 v[152:153], v[152:153], 0, s[6:7]
	v_lshl_add_u64 v[154:155], v[154:155], 0, s[8:9]
	v_lshl_add_u64 v[156:157], v[156:157], 0, s[10:11]
	s_cmp_eq_u32 s16, 31
	s_mov_b32 s5, s16
	s_cbranch_scc0 .LBB0_602
; #define LAS __attribute__((address_space(3)))
; __device__ __forceinline__ f32x4 mfma16(const bf16x8& a, const bf16x8& b, const f32x4& c) { return __builtin_amdgcn_mfma_f32_16x16x32_bf16(a, b, c, 0, 0, 0); }
; template <bool PROMPT>
; __device__ __forceinline__ void scan_block(const Params& p, LAS unsigned char* lds, int chs0, int nsteps, const float* s0, float* sfin, int rowbase, int ntok, int h, int half) {
;     ...
;         const LAS unsigned char* B = lds + (n & 1) * SC_BUF;
;         bf16x8 Sb[4];
; #pragma unroll
;         for (int P = 0; P < 4; ++P) Sb[P] = pack8(ST[2 * P], ST[2 * P + 1]);
;         f32x4 ws[4], qs[4];
;         bf16x8 fa[8];
; #pragma unroll
;         for (int tt = 0; tt < 4; ++tt) {
; #pragma unroll
;             for (int P = 0; P < 4; ++P) { fa[P] = *(const LAS bf16x8*)(B + SC_W + (16 * tt + fr) * 272 + (32 * P + 8 * fq) * 2);
;                                           fa[4 + P] = *(const LAS bf16x8*)(B + SC_QS + (16 * tt + fr) * 272 + (32 * P + 8 * fq) * 2); }
;             __builtin_amdgcn_sched_barrier(0);
;             ws[tt] = (f32x4){0.f, 0.f, 0.f, 0.f}; qs[tt] = (f32x4){0.f, 0.f, 0.f, 0.f};
; #pragma unroll
;             for (int P = 0; P < 4; ++P) { ws[tt] = mfma16(fa[P], Sb[P], ws[tt]); qs[tt] = mfma16(fa[4 + P], Sb[P], qs[tt]); }
;             __builtin_amdgcn_sched_barrier(0);
;         }
;     ...
; #pragma unroll
;     for (int T = 0; T < 8; ++T)
; #pragma unroll
;         for (int jj = 0; jj < 4; ++jj) sfin[(size_t)(16 * T + 4 * fq + jj) * 128 + dv] = ST[T][jj];
	s_lshl_b32 s4, s33, 8
	s_and_b32 s4, s4, 0x3800
	s_lshl_b32 s0, s0, 16
	s_add_u32 s0, s48, s0
	v_or_b32_e32 v48, s1, v160
	s_addc_u32 s1, s49, 0
	v_or_b32_e32 v132, s4, v170
	s_add_u32 s4, s0, 0x4300000
	v_lshlrev_b32_e32 v133, 1, v48
	s_addc_u32 s5, s1, 0
	s_add_i32 s0, 0, 0x13800
	v_add3_u32 v124, 0, v169, v163
	v_add3_u32 v88, s0, v169, v163
	ds_read_b128 v[60:63], v124 offset:62464
	ds_read_b128 v[64:67], v124 offset:62528
	ds_read_b128 v[68:71], v88
	ds_read_b128 v[72:75], v88 offset:64
	ds_read_b128 v[76:79], v124 offset:62592
	ds_read_b128 v[80:83], v124 offset:62656
	ds_read_b128 v[84:87], v88 offset:128
	ds_read_b128 v[88:91], v88 offset:192
	v_cvt_pk_bf16_f32 v48, v28, v29
	v_cvt_pk_bf16_f32 v49, v30, v31
	v_cvt_pk_bf16_f32 v50, v24, v25
	v_cvt_pk_bf16_f32 v51, v26, v27
	v_cvt_pk_bf16_f32 v52, v20, v21
	v_cvt_pk_bf16_f32 v53, v22, v23
	v_cvt_pk_bf16_f32 v54, v16, v17
	v_cvt_pk_bf16_f32 v55, v18, v19
	v_cvt_pk_bf16_f32 v56, v44, v45
	v_cvt_pk_bf16_f32 v57, v46, v47
	v_cvt_pk_bf16_f32 v58, v40, v41
	v_cvt_pk_bf16_f32 v59, v42, v43
	v_cvt_pk_bf16_f32 v92, v36, v37
	v_cvt_pk_bf16_f32 v93, v38, v39
	v_cvt_pk_bf16_f32 v94, v32, v33
	v_cvt_pk_bf16_f32 v95, v34, v35
	s_waitcnt lgkmcnt(7)
	v_mfma_f32_16x16x32_bf16 v[60:63], v[60:63], v[48:51], 0
	s_waitcnt lgkmcnt(5)
	v_mfma_f32_16x16x32_bf16 v[68:71], v[68:71], v[48:51], 0
	v_mfma_f32_16x16x32_bf16 v[60:63], v[64:67], v[52:55], v[60:63]
	s_waitcnt lgkmcnt(4)
	v_mfma_f32_16x16x32_bf16 v[64:67], v[72:75], v[52:55], v[68:71]
	s_waitcnt lgkmcnt(3)
	v_mfma_f32_16x16x32_bf16 v[60:63], v[76:79], v[56:59], v[60:63]
	s_waitcnt lgkmcnt(1)
	v_mfma_f32_16x16x32_bf16 v[64:67], v[84:87], v[56:59], v[64:67]
	v_mfma_f32_16x16x32_bf16 v[96:99], v[80:83], v[92:95], v[60:63]
	s_waitcnt lgkmcnt(0)
	v_mfma_f32_16x16x32_bf16 v[84:87], v[88:91], v[92:95], v[64:67]
	v_add_u32_e32 v80, 0x1100, v124
	v_add3_u32 v100, s0, v168, v163
	s_nop 0
	ds_read_b128 v[60:63], v80 offset:62464
	s_nop 0
	ds_read_b128 v[64:67], v80 offset:62528
	ds_read_b128 v[68:71], v100
	ds_read_b128 v[72:75], v100 offset:64
	ds_read_b128 v[76:79], v80 offset:62592
	ds_read_b128 v[80:83], v80 offset:62656
	ds_read_b128 v[88:91], v100 offset:128
	ds_read_b128 v[100:103], v100 offset:192
	s_waitcnt lgkmcnt(7)
	v_mfma_f32_16x16x32_bf16 v[60:63], v[60:63], v[48:51], 0
	s_waitcnt lgkmcnt(5)
	v_mfma_f32_16x16x32_bf16 v[68:71], v[68:71], v[48:51], 0
	v_mfma_f32_16x16x32_bf16 v[60:63], v[64:67], v[52:55], v[60:63]
	s_waitcnt lgkmcnt(4)
	v_mfma_f32_16x16x32_bf16 v[64:67], v[72:75], v[52:55], v[68:71]
	s_waitcnt lgkmcnt(3)
	v_mfma_f32_16x16x32_bf16 v[60:63], v[76:79], v[56:59], v[60:63]
	s_waitcnt lgkmcnt(1)
	v_mfma_f32_16x16x32_bf16 v[64:67], v[88:91], v[56:59], v[64:67]
	v_mfma_f32_16x16x32_bf16 v[104:107], v[80:83], v[92:95], v[60:63]
	s_waitcnt lgkmcnt(0)
	v_mfma_f32_16x16x32_bf16 v[100:103], v[100:103], v[92:95], v[64:67]
	v_add_u32_e32 v80, 0x2200, v124
	v_add3_u32 v108, s0, v167, v163
	s_nop 0
	ds_read_b128 v[60:63], v80 offset:62464
	s_nop 0
	ds_read_b128 v[64:67], v80 offset:62528
	ds_read_b128 v[68:71], v108
	ds_read_b128 v[72:75], v108 offset:64
	ds_read_b128 v[76:79], v80 offset:62592
	ds_read_b128 v[80:83], v80 offset:62656
	ds_read_b128 v[88:91], v108 offset:128
	ds_read_b128 v[108:111], v108 offset:192
	s_waitcnt lgkmcnt(7)
	v_mfma_f32_16x16x32_bf16 v[60:63], v[60:63], v[48:51], 0
	s_waitcnt lgkmcnt(5)
	v_mfma_f32_16x16x32_bf16 v[68:71], v[68:71], v[48:51], 0
	v_mfma_f32_16x16x32_bf16 v[60:63], v[64:67], v[52:55], v[60:63]
	s_waitcnt lgkmcnt(4)
	v_mfma_f32_16x16x32_bf16 v[64:67], v[72:75], v[52:55], v[68:71]
	s_waitcnt lgkmcnt(3)
	v_mfma_f32_16x16x32_bf16 v[60:63], v[76:79], v[56:59], v[60:63]
	s_waitcnt lgkmcnt(1)
	v_mfma_f32_16x16x32_bf16 v[64:67], v[88:91], v[56:59], v[64:67]
	v_mfma_f32_16x16x32_bf16 v[120:123], v[80:83], v[92:95], v[60:63]
	s_waitcnt lgkmcnt(0)
	v_mfma_f32_16x16x32_bf16 v[80:83], v[108:111], v[92:95], v[64:67]
	v_add_u32_e32 v88, 0x3300, v124
	v_add3_u32 v124, s0, v166, v163
	s_nop 0
	ds_read_b128 v[60:63], v88 offset:62464
	s_nop 0
	ds_read_b128 v[64:67], v88 offset:62528
	ds_read_b128 v[68:71], v124
	ds_read_b128 v[72:75], v124 offset:64
	ds_read_b128 v[76:79], v88 offset:62592
	ds_read_b128 v[88:91], v88 offset:62656
	ds_read_b128 v[108:111], v124 offset:128
	ds_read_b128 v[124:127], v124 offset:192
	s_waitcnt lgkmcnt(7)
	v_mfma_f32_16x16x32_bf16 v[60:63], v[60:63], v[48:51], 0
	s_waitcnt lgkmcnt(5)
	v_mfma_f32_16x16x32_bf16 v[48:51], v[68:71], v[48:51], 0
	v_mfma_f32_16x16x32_bf16 v[60:63], v[64:67], v[52:55], v[60:63]
	s_waitcnt lgkmcnt(4)
	v_mfma_f32_16x16x32_bf16 v[48:51], v[72:75], v[52:55], v[48:51]
	s_waitcnt lgkmcnt(3)
	v_mfma_f32_16x16x32_bf16 v[52:55], v[76:79], v[56:59], v[60:63]
	s_waitcnt lgkmcnt(1)
	v_mfma_f32_16x16x32_bf16 v[48:51], v[108:111], v[56:59], v[48:51]
	v_mfma_f32_16x16x32_bf16 v[108:111], v[88:91], v[92:95], v[52:55]
	s_waitcnt lgkmcnt(0)
	v_mfma_f32_16x16x32_bf16 v[88:91], v[124:127], v[92:95], v[48:51]
	s_add_i32 s0, 0, 0x1c400
	v_add3_u32 v76, s0, v163, v164
	s_nop 2
	ds_read_b128 v[48:51], v76
	ds_read_b128 v[52:55], v76 offset:64
	ds_read_b128 v[56:59], v76 offset:2304
	ds_read_b128 v[60:63], v76 offset:2368
	ds_read_b128 v[64:67], v76 offset:4608
	ds_read_b128 v[68:71], v76 offset:4672
	ds_read_b128 v[72:75], v76 offset:6912
	ds_read_b128 v[76:79], v76 offset:6976
	s_waitcnt vmcnt(16)
; #define LAS __attribute__((address_space(3)))
; __device__ __forceinline__ float bf2f(short b) { return __uint_as_float(((unsigned)(unsigned short)b) << 16); }
; template <bool PROMPT>
; __device__ __forceinline__ void scan_block(const Params& p, LAS unsigned char* lds, int chs0, int nsteps, const float* s0, float* sfin, int rowbase, int ntok, int h, int half) {
;     ...
;             for (int jj = 0; jj < 4; ++jj) { vn[tt][jj] = bf2f(u4[tt][jj]) - ws[tt][jj]; vd[tt][jj] = vn[tt][jj] * __expf(Glc - g4[tt][jj]); }
;         bf16x8 Vb[2], Vd[2];
; #pragma unroll
;         for (int u = 0; u < 2; ++u) { Vb[u] = pack8(vn[2 * u], vn[2 * u + 1]); Vd[u] = pack8(vd[2 * u], vd[2 * u + 1]); }
;         f32x4 o[4];
; #pragma unroll
;         for (int tt = 0; tt < 4; ++tt)
; #pragma unroll
;             for (int jj = 0; jj < 4; ++jj) o[tt][jj] = qs[tt][jj] * __expf(g4[tt][jj]);
;         const float gt = __expf(Glc);
; #pragma unroll
;         for (int T = 0; T < 8; ++T) ST[T] = ST[T] * gt;
;         __builtin_amdgcn_sched_barrier(0);
; #pragma unroll
;         for (int T = 0; T < 4; ++T)
; #pragma unroll
;             for (int u = 0; u < 2; ++u) fk[T * 2 + u] = *(const LAS bf16x8*)(B + SC_KT + (16 * T + fr) * 144 + (32 * u + 8 * fq) * 2);
	v_sub_f32_e32 v92, v165, v12
	v_sub_f32_e32 v93, v165, v13
	v_mul_f32_e32 v92, 0x3fb8aa3b, v92
	v_mul_f32_e32 v93, 0x3fb8aa3b, v93
	v_exp_f32_e32 v92, v92
	v_exp_f32_e32 v93, v93
	v_and_b32_e32 v95, 0xffff0000, v118
	v_lshlrev_b32_e32 v94, 16, v118
	v_pk_add_f32 v[94:95], v[94:95], v[96:97] neg_lo:[0,1] neg_hi:[0,1]
	v_and_b32_e32 v125, 0xffff0000, v119
	v_pk_mul_f32 v[96:97], v[92:93], v[94:95]
	v_sub_f32_e32 v92, v165, v14
	v_sub_f32_e32 v93, v165, v15
	v_mul_f32_e32 v92, 0x3fb8aa3b, v92
	v_mul_f32_e32 v93, 0x3fb8aa3b, v93
	v_exp_f32_e32 v92, v92
	v_exp_f32_e32 v93, v93
	v_lshlrev_b32_e32 v124, 16, v119
	v_pk_add_f32 v[98:99], v[124:125], v[98:99] neg_lo:[0,1] neg_hi:[0,1]
	v_and_b32_e32 v125, 0xffff0000, v116
	v_pk_mul_f32 v[118:119], v[92:93], v[98:99]
	v_sub_f32_e32 v92, v165, v8
	v_sub_f32_e32 v93, v165, v9
	v_mul_f32_e32 v92, 0x3fb8aa3b, v92
	v_mul_f32_e32 v93, 0x3fb8aa3b, v93
	v_exp_f32_e32 v92, v92
	v_exp_f32_e32 v93, v93
	v_lshlrev_b32_e32 v124, 16, v116
	v_pk_add_f32 v[104:105], v[124:125], v[104:105] neg_lo:[0,1] neg_hi:[0,1]
	v_and_b32_e32 v127, 0xffff0000, v117
	v_pk_mul_f32 v[124:125], v[92:93], v[104:105]
	v_sub_f32_e32 v92, v165, v10
	v_sub_f32_e32 v93, v165, v11
	v_mul_f32_e32 v92, 0x3fb8aa3b, v92
	v_mul_f32_e32 v93, 0x3fb8aa3b, v93
	v_exp_f32_e32 v92, v92
	v_exp_f32_e32 v93, v93
	v_lshlrev_b32_e32 v126, 16, v117
	v_pk_add_f32 v[106:107], v[126:127], v[106:107] neg_lo:[0,1] neg_hi:[0,1]
	v_and_b32_e32 v127, 0xffff0000, v114
	v_pk_mul_f32 v[116:117], v[92:93], v[106:107]
	v_sub_f32_e32 v92, v165, v4
	v_sub_f32_e32 v93, v165, v5
	v_mul_f32_e32 v92, 0x3fb8aa3b, v92
	v_mul_f32_e32 v93, 0x3fb8aa3b, v93
	v_exp_f32_e32 v92, v92
	v_exp_f32_e32 v93, v93
	v_lshlrev_b32_e32 v126, 16, v114
	v_pk_add_f32 v[120:121], v[126:127], v[120:121] neg_lo:[0,1] neg_hi:[0,1]
	v_and_b32_e32 v129, 0xffff0000, v115
	v_pk_mul_f32 v[126:127], v[92:93], v[120:121]
	v_sub_f32_e32 v92, v165, v6
	v_sub_f32_e32 v93, v165, v7
	v_mul_f32_e32 v92, 0x3fb8aa3b, v92
	v_mul_f32_e32 v93, 0x3fb8aa3b, v93
	v_exp_f32_e32 v92, v92
	v_exp_f32_e32 v93, v93
	v_lshlrev_b32_e32 v128, 16, v115
	v_pk_add_f32 v[114:115], v[128:129], v[122:123] neg_lo:[0,1] neg_hi:[0,1]
	v_and_b32_e32 v129, 0xffff0000, v112
	v_pk_mul_f32 v[122:123], v[92:93], v[114:115]
	v_sub_f32_e32 v92, v165, v0
	v_sub_f32_e32 v93, v165, v1
	v_mul_f32_e32 v92, 0x3fb8aa3b, v92
	v_mul_f32_e32 v93, 0x3fb8aa3b, v93
	v_exp_f32_e32 v92, v92
	v_exp_f32_e32 v93, v93
	v_lshlrev_b32_e32 v128, 16, v112
	v_pk_add_f32 v[108:109], v[128:129], v[108:109] neg_lo:[0,1] neg_hi:[0,1]
	v_and_b32_e32 v131, 0xffff0000, v113
	v_pk_mul_f32 v[128:129], v[92:93], v[108:109]
	v_sub_f32_e32 v92, v165, v2
	v_sub_f32_e32 v93, v165, v3
	v_mul_f32_e32 v92, 0x3fb8aa3b, v92
	v_mul_f32_e32 v93, 0x3fb8aa3b, v93
	v_exp_f32_e32 v92, v92
	v_exp_f32_e32 v93, v93
	v_lshlrev_b32_e32 v130, 16, v113
	v_mul_f32_e32 v12, 0x3fb8aa3b, v12
	v_mul_f32_e32 v13, 0x3fb8aa3b, v13
	v_pk_add_f32 v[110:111], v[130:131], v[110:111] neg_lo:[0,1] neg_hi:[0,1]
	v_exp_f32_e32 v12, v12
	v_exp_f32_e32 v13, v13
	v_mul_f32_e32 v6, 0x3fb8aa3b, v6
	v_mul_f32_e32 v7, 0x3fb8aa3b, v7
	v_pk_mul_f32 v[112:113], v[92:93], v[110:111]
	v_mul_f32_e32 v8, 0x3fb8aa3b, v8
	v_exp_f32_e32 v6, v6
	v_exp_f32_e32 v7, v7
	v_cvt_pk_bf16_f32 v92, v94, v95
	v_cvt_pk_bf16_f32 v95, v106, v107
	v_cvt_pk_bf16_f32 v107, v110, v111
	v_cvt_pk_bf16_f32 v111, v112, v113
	v_mul_f32_e32 v14, 0x3fb8aa3b, v14
	v_mul_f32_e32 v15, 0x3fb8aa3b, v15
	v_exp_f32_e32 v112, v8
	v_mul_f32_e32 v8, 0x3fb8aa3b, v9
	v_mul_f32_e32 v9, 0x3fb8aa3b, v10
	v_cvt_pk_bf16_f32 v94, v104, v105
	v_cvt_pk_bf16_f32 v105, v114, v115
	v_exp_f32_e32 v14, v14
	v_exp_f32_e32 v15, v15
	v_exp_f32_e32 v114, v9
	v_mul_f32_e32 v9, 0x3fb8aa3b, v11
	v_mul_f32_e32 v4, 0x3fb8aa3b, v4
	v_exp_f32_e32 v115, v9
	v_exp_f32_e32 v113, v8
	v_pk_mul_f32 v[8:9], v[12:13], v[84:85]
	v_exp_f32_e32 v84, v4
	v_mul_f32_e32 v4, 0x3fb8aa3b, v5
	v_mul_f32_e32 v2, 0x3fb8aa3b, v2
	v_exp_f32_e32 v85, v4
	v_pk_mul_f32 v[4:5], v[6:7], v[82:83]
	v_exp_f32_e32 v6, v2
	v_mul_f32_e32 v2, 0x3fb8aa3b, v3
	v_mul_f32_e32 v0, 0x3fb8aa3b, v0
	v_mul_f32_e32 v1, 0x3fb8aa3b, v1
	v_exp_f32_e32 v7, v2
	v_mul_f32_e32 v2, 0x3fb8aa3b, v165
	v_pk_mul_f32 v[10:11], v[14:15], v[86:87]
	v_exp_f32_e32 v0, v0
	v_exp_f32_e32 v1, v1
	v_exp_f32_e32 v86, v2
	v_cvt_pk_bf16_f32 v93, v98, v99
	v_cvt_pk_bf16_f32 v96, v96, v97
	v_cvt_pk_bf16_f32 v97, v118, v119
	v_cvt_pk_bf16_f32 v98, v124, v125
	v_cvt_pk_bf16_f32 v99, v116, v117
	v_cvt_pk_bf16_f32 v104, v120, v121
	v_cvt_pk_bf16_f32 v106, v108, v109
	v_cvt_pk_bf16_f32 v108, v126, v127
	v_cvt_pk_bf16_f32 v109, v122, v123
	v_cvt_pk_bf16_f32 v110, v128, v129
	v_pk_mul_f32 v[14:15], v[114:115], v[102:103]
	v_pk_mul_f32 v[12:13], v[112:113], v[100:101]
	v_pk_mul_f32 v[2:3], v[84:85], v[80:81]
	v_pk_mul_f32 v[82:83], v[6:7], v[90:91]
	v_pk_mul_f32 v[80:81], v[0:1], v[88:89]
	v_pk_mul_f32 v[30:31], v[86:87], v[30:31] op_sel_hi:[0,1]
	v_pk_mul_f32 v[28:29], v[86:87], v[28:29] op_sel_hi:[0,1]
	v_pk_mul_f32 v[26:27], v[86:87], v[26:27] op_sel_hi:[0,1]
	v_pk_mul_f32 v[24:25], v[86:87], v[24:25] op_sel_hi:[0,1]
	v_pk_mul_f32 v[22:23], v[86:87], v[22:23] op_sel_hi:[0,1]
	v_pk_mul_f32 v[20:21], v[86:87], v[20:21] op_sel_hi:[0,1]
	v_pk_mul_f32 v[18:19], v[86:87], v[18:19] op_sel_hi:[0,1]
	v_pk_mul_f32 v[16:17], v[86:87], v[16:17] op_sel_hi:[0,1]
	v_pk_mul_f32 v[46:47], v[86:87], v[46:47] op_sel_hi:[0,1]
	v_pk_mul_f32 v[44:45], v[86:87], v[44:45] op_sel_hi:[0,1]
	v_pk_mul_f32 v[42:43], v[86:87], v[42:43] op_sel_hi:[0,1]
	v_pk_mul_f32 v[40:41], v[86:87], v[40:41] op_sel_hi:[0,1]
	v_pk_mul_f32 v[38:39], v[86:87], v[38:39] op_sel_hi:[0,1]
	v_pk_mul_f32 v[36:37], v[86:87], v[36:37] op_sel_hi:[0,1]
	v_pk_mul_f32 v[34:35], v[86:87], v[34:35] op_sel_hi:[0,1]
	v_pk_mul_f32 v[32:33], v[86:87], v[32:33] op_sel_hi:[0,1]
	s_add_i32 s0, 0, 0x17c00
	v_add3_u32 v0, s0, v163, v164
	ds_read_b128 v[84:87], v0
	ds_read_b128 v[88:91], v0 offset:64
	ds_read_b128 v[100:103], v0 offset:2304
	ds_read_b128 v[112:115], v0 offset:2368
	ds_read_b128 v[116:119], v0 offset:4608
	ds_read_b128 v[120:123], v0 offset:4672
	ds_read_b128 v[124:127], v0 offset:6912
	ds_read_b128 v[128:131], v0 offset:6976
	s_waitcnt lgkmcnt(14)
; #define LAS __attribute__((address_space(3)))
; __device__ __forceinline__ bf16_t f2bf(float f) { return (bf16_t)(cvt_pk_bf16(f, 0.f) & 0xffffu); }
; __device__ __forceinline__ f32x4 mfma16(const bf16x8& a, const bf16x8& b, const f32x4& c) { return __builtin_amdgcn_mfma_f32_16x16x32_bf16(a, b, c, 0, 0, 0); }
; template <bool PROMPT>
; __device__ __forceinline__ void scan_block(const Params& p, LAS unsigned char* lds, int chs0, int nsteps, const float* s0, float* sfin, int rowbase, int ntok, int h, int half) {
;     ...
;         for (int tt = 0; tt < 4; ++tt)
; #pragma unroll
;             for (int u = 0; u < 2; ++u) o[tt] = mfma16(fq_[tt * 2 + u], Vb[u], o[tt]);
;         __builtin_amdgcn_sched_barrier(0);
; #pragma unroll
;         for (int T = 0; T < 4; ++T)
; #pragma unroll
;             for (int u = 0; u < 2; ++u) fq_[T * 2 + u] = *(const LAS bf16x8*)(B + SC_KT + (16 * (4 + T) + fr) * 144 + (32 * u + 8 * fq) * 2);
;         __builtin_amdgcn_sched_barrier(0);
; #pragma unroll
;         for (int T = 0; T < 4; ++T)
; #pragma unroll
;             for (int u = 0; u < 2; ++u) ST[T] = mfma16(fk[T * 2 + u], Vd[u], ST[T]);
;         __builtin_amdgcn_sched_barrier(0);
; #pragma unroll
;         for (int T = 0; T < 4; ++T)
; #pragma unroll
;             for (int u = 0; u < 2; ++u) ST[4 + T] = mfma16(fq_[T * 2 + u], Vd[u], ST[4 + T]);
; #pragma unroll
;         for (int tt = 0; tt < 4; ++tt)
; #pragma unroll
;             for (int jj = 0; jj < 4; ++jj) {
;                 const int tok = 16 * tt + 4 * fq + jj;
;                 if constexpr (PROMPT) {
;                     const unsigned row = (unsigned)(rowbase + n * 64 + tok);
;                     CAT[row * (unsigned)DM + (unsigned)(512 + h * 128 + dv)] = f2bf(o[tt][jj]);
;                 } else {
;                     const unsigned row = (unsigned)(rowbase + n * 64 + (tok < ntok ? tok : 0));
;                     if (tok < ntok) CAT[row * (unsigned)DM + (unsigned)(512 + h * 128 + dv)] = f2bf(o[tt][jj]);
;                 }
;             }
	v_mfma_f32_16x16x32_bf16 v[6:9], v[48:51], v[92:95], v[8:11]
	s_waitcnt lgkmcnt(13)
	v_mfma_f32_16x16x32_bf16 v[10:13], v[56:59], v[92:95], v[12:15]
	s_waitcnt lgkmcnt(11)
	v_mfma_f32_16x16x32_bf16 v[0:3], v[64:67], v[92:95], v[2:5]
	s_waitcnt lgkmcnt(9)
	v_mfma_f32_16x16x32_bf16 v[48:51], v[72:75], v[92:95], v[80:83]
	v_mfma_f32_16x16x32_bf16 v[6:9], v[52:55], v[104:107], v[6:9]
	v_mfma_f32_16x16x32_bf16 v[10:13], v[60:63], v[104:107], v[10:13]
	v_mfma_f32_16x16x32_bf16 v[0:3], v[68:71], v[104:107], v[0:3]
	s_waitcnt lgkmcnt(8)
	v_mfma_f32_16x16x32_bf16 v[48:51], v[76:79], v[104:107], v[48:51]
	s_add_i32 s0, 0, 0x1a000
	v_add3_u32 v4, s0, v163, v164
	ds_read_b128 v[52:55], v4
	ds_read_b128 v[56:59], v4 offset:64
	ds_read_b128 v[60:63], v4 offset:2304
	ds_read_b128 v[64:67], v4 offset:2368
	ds_read_b128 v[68:71], v4 offset:4608
	ds_read_b128 v[72:75], v4 offset:4672
	ds_read_b128 v[76:79], v4 offset:6912
	ds_read_b128 v[80:83], v4 offset:6976
	s_waitcnt lgkmcnt(14)
	v_mfma_f32_16x16x32_bf16 v[28:31], v[84:87], v[96:99], v[28:31]
	s_waitcnt lgkmcnt(13)
	v_mfma_f32_16x16x32_bf16 v[24:27], v[100:103], v[96:99], v[24:27]
	s_waitcnt lgkmcnt(11)
	v_mfma_f32_16x16x32_bf16 v[20:23], v[116:119], v[96:99], v[20:23]
	s_waitcnt lgkmcnt(9)
	v_mfma_f32_16x16x32_bf16 v[14:17], v[124:127], v[96:99], v[16:19]
	v_mfma_f32_16x16x32_bf16 v[28:31], v[88:91], v[108:111], v[28:31]
	v_mfma_f32_16x16x32_bf16 v[24:27], v[112:115], v[108:111], v[24:27]
	v_mfma_f32_16x16x32_bf16 v[20:23], v[120:123], v[108:111], v[20:23]
	s_waitcnt lgkmcnt(8)
	v_mfma_f32_16x16x32_bf16 v[14:17], v[128:131], v[108:111], v[14:17]
	v_cvt_pk_bf16_f32 v6, v6, s0
	v_lshlrev_b32_e32 v4, 11, v132
	s_movk_i32 s0, 0x400
	v_or3_b32 v18, v133, v4, s0
	v_mov_b32_e32 v19, 0
	s_waitcnt lgkmcnt(7)
	v_mfma_f32_16x16x32_bf16 v[44:47], v[52:55], v[96:99], v[44:47]
	v_lshl_add_u64 v[52:53], s[50:51], 0, v[18:19]
	s_mov_b32 s0, 0x9f20000
	v_add_co_u32_e32 v4, vcc, s0, v52
	s_mov_b32 s0, 0x9f21000
	s_nop 0
	v_addc_co_u32_e32 v5, vcc, 0, v53, vcc
	v_add_co_u32_e32 v54, vcc, s0, v52
	v_cvt_pk_bf16_f32 v8, v8, s0
	s_nop 0
	v_addc_co_u32_e32 v55, vcc, 0, v53, vcc
	global_store_short v[54:55], v6, off offset:-4096
	v_cvt_pk_bf16_f32 v6, v7, s0
	global_store_short v[54:55], v8, off
	v_cvt_pk_bf16_f32 v8, v9, s0
	v_cvt_pk_bf16_f32 v10, v10, s0
	s_mov_b32 s0, 0x9f28000
	global_store_short v[54:55], v8, off offset:2048
	v_add_co_u32_e32 v8, vcc, s0, v52
	s_mov_b32 s0, 0x9f29000
	s_nop 0
	v_addc_co_u32_e32 v9, vcc, 0, v53, vcc
	global_store_short v[4:5], v6, off offset:2048
	s_waitcnt lgkmcnt(1)
	v_mfma_f32_16x16x32_bf16 v[4:7], v[76:79], v[96:99], v[32:35]
	v_cvt_pk_bf16_f32 v0, v0, s0
	s_nop 1
	v_add_co_u32_e32 v32, vcc, s0, v52
	v_mfma_f32_16x16x32_bf16 v[44:47], v[56:59], v[108:111], v[44:47]
	s_nop 0
	v_addc_co_u32_e32 v33, vcc, 0, v53, vcc
	global_store_short v[32:33], v10, off offset:-4096
	v_cvt_pk_bf16_f32 v10, v11, s0
	global_store_short v[8:9], v10, off offset:2048
	v_cvt_pk_bf16_f32 v8, v12, s0
	global_store_short v[32:33], v8, off
	v_cvt_pk_bf16_f32 v8, v13, s0
	s_mov_b32 s0, 0x9f30000
	global_store_short v[32:33], v8, off offset:2048
	v_add_co_u32_e32 v8, vcc, s0, v52
	s_mov_b32 s0, 0x9f31000
	s_nop 0
	v_addc_co_u32_e32 v9, vcc, 0, v53, vcc
	v_add_co_u32_e32 v10, vcc, s0, v52
	v_mfma_f32_16x16x32_bf16 v[40:43], v[60:63], v[96:99], v[40:43]
	s_nop 0
	v_addc_co_u32_e32 v11, vcc, 0, v53, vcc
	global_store_short v[10:11], v0, off offset:-4096
	v_cvt_pk_bf16_f32 v0, v1, s0
	global_store_short v[8:9], v0, off offset:2048
	v_cvt_pk_bf16_f32 v0, v2, s0
	global_store_short v[10:11], v0, off
	v_cvt_pk_bf16_f32 v0, v3, s0
	v_cvt_pk_bf16_f32 v8, v48, s0
	s_mov_b32 s0, 0x9f38000
	global_store_short v[10:11], v0, off offset:2048
	v_add_co_u32_e32 v0, vcc, s0, v52
	s_mov_b32 s0, 0x9f39000
	s_nop 0
	v_addc_co_u32_e32 v1, vcc, 0, v53, vcc
	v_add_co_u32_e32 v2, vcc, s0, v52
	v_mfma_f32_16x16x32_bf16 v[36:39], v[68:71], v[96:99], v[36:39]
	s_nop 0
	v_addc_co_u32_e32 v3, vcc, 0, v53, vcc
	global_store_short v[2:3], v8, off offset:-4096
	v_cvt_pk_bf16_f32 v8, v49, s0
	global_store_short v[0:1], v8, off offset:2048
	v_cvt_pk_bf16_f32 v0, v50, s0
	global_store_short v[2:3], v0, off
	v_cvt_pk_bf16_f32 v0, v51, s0
	global_store_short v[2:3], v0, off offset:2048
	v_lshlrev_b32_e32 v0, 2, v160
	v_lshl_or_b32 v18, v162, 11, v0
	v_lshl_add_u64 v[0:1], s[4:5], 0, v[18:19]
	s_movk_i32 s0, 0x2000
	v_add_co_u32_e32 v2, vcc, s0, v0
	s_movk_i32 s0, 0x4000
	s_nop 0
	v_addc_co_u32_e32 v3, vcc, 0, v1, vcc
	s_waitcnt lgkmcnt(0)
	s_barrier
; __device__ __forceinline__ f32x4 mfma16(const bf16x8& a, const bf16x8& b, const f32x4& c) { return __builtin_amdgcn_mfma_f32_16x16x32_bf16(a, b, c, 0, 0, 0); }
; template <bool PROMPT>
; __device__ __forceinline__ void scan_block(const Params& p, LAS unsigned char* lds, int chs0, int nsteps, const float* s0, float* sfin, int rowbase, int ntok, int h, int half) {
;     ...
;         for (int T = 0; T < 4; ++T)
; #pragma unroll
;             for (int u = 0; u < 2; ++u) ST[T] = mfma16(fk[T * 2 + u], Vd[u], ST[T]);
;         __builtin_amdgcn_sched_barrier(0);
; #pragma unroll
;         for (int T = 0; T < 4; ++T)
; #pragma unroll
;             for (int u = 0; u < 2; ++u) ST[4 + T] = mfma16(fq_[T * 2 + u], Vd[u], ST[4 + T]);
;     ...
; #pragma unroll
;     for (int T = 0; T < 8; ++T)
; #pragma unroll
;         for (int jj = 0; jj < 4; ++jj) sfin[(size_t)(16 * T + 4 * fq + jj) * 128 + dv] = ST[T][jj];
	global_store_dword v18, v28, s[4:5]
	global_store_dword v18, v29, s[4:5] offset:512
	global_store_dword v18, v30, s[4:5] offset:1024
	global_store_dword v18, v31, s[4:5] offset:1536
	global_store_dword v[2:3], v24, off
	global_store_dword v[2:3], v25, off offset:512
	global_store_dword v[2:3], v26, off offset:1024
	global_store_dword v[2:3], v27, off offset:1536
	v_add_co_u32_e32 v2, vcc, s0, v0
	v_lshl_or_b32 v8, v161, 9, v160
	s_nop 0
	v_addc_co_u32_e32 v3, vcc, 0, v1, vcc
	v_or_b32_e32 v18, 0x1800, v8
	global_store_dword v[2:3], v20, off
	global_store_dword v[2:3], v21, off offset:512
	global_store_dword v[2:3], v22, off offset:1024
	global_store_dword v[2:3], v23, off offset:1536
	v_lshl_add_u64 v[2:3], v[18:19], 2, s[4:5]
	v_or_b32_e32 v18, 0x1880, v8
	global_store_dword v[2:3], v14, off
	v_lshl_add_u64 v[2:3], v[18:19], 2, s[4:5]
	v_or_b32_e32 v18, 0x1900, v8
	global_store_dword v[2:3], v15, off
	v_lshl_add_u64 v[2:3], v[18:19], 2, s[4:5]
	v_or_b32_e32 v18, 0x1980, v8
	global_store_dword v[2:3], v16, off
	v_lshl_add_u64 v[2:3], v[18:19], 2, s[4:5]
	s_mov_b32 s0, 0x8000
	global_store_dword v[2:3], v17, off
	v_add_co_u32_e32 v2, vcc, s0, v0
	s_mov_b32 s0, 0xa000
	s_nop 0
	v_addc_co_u32_e32 v3, vcc, 0, v1, vcc
	v_mfma_f32_16x16x32_bf16 v[40:43], v[64:67], v[108:111], v[40:43]
	global_store_dword v[2:3], v44, off
	global_store_dword v[2:3], v45, off offset:512
	global_store_dword v[2:3], v46, off offset:1024
	global_store_dword v[2:3], v47, off offset:1536
	v_add_co_u32_e32 v2, vcc, s0, v0
	v_mfma_f32_16x16x32_bf16 v[36:39], v[72:75], v[108:111], v[36:39]
	s_nop 0
	v_addc_co_u32_e32 v3, vcc, 0, v1, vcc
	s_mov_b32 s0, 0xc000
	s_waitcnt lgkmcnt(0)
	v_mfma_f32_16x16x32_bf16 v[4:7], v[80:83], v[108:111], v[4:7]
	v_add_co_u32_e32 v0, vcc, s0, v0
	v_or_b32_e32 v18, 0x3800, v8
	s_nop 0
	v_addc_co_u32_e32 v1, vcc, 0, v1, vcc
	global_store_dword v[2:3], v40, off
	global_store_dword v[2:3], v41, off offset:512
	global_store_dword v[2:3], v42, off offset:1024
	global_store_dword v[2:3], v43, off offset:1536
	global_store_dword v[0:1], v36, off
	global_store_dword v[0:1], v37, off offset:512
	global_store_dword v[0:1], v38, off offset:1024
	global_store_dword v[0:1], v39, off offset:1536
	v_lshl_add_u64 v[0:1], v[18:19], 2, s[4:5]
	v_or_b32_e32 v18, 0x3880, v8
	global_store_dword v[0:1], v4, off
	v_lshl_add_u64 v[0:1], v[18:19], 2, s[4:5]
	v_or_b32_e32 v18, 0x3900, v8
	global_store_dword v[0:1], v5, off
	v_lshl_add_u64 v[0:1], v[18:19], 2, s[4:5]
	v_or_b32_e32 v18, 0x3980, v8
	global_store_dword v[0:1], v6, off
	v_lshl_add_u64 v[0:1], v[18:19], 2, s[4:5]
	global_store_dword v[0:1], v7, off
